# combo6 = combo4 + XCD-local grid barrier (no L2 write-back, no cross-XCD round) at the 7 same-XCD GEMM seams, enabled only when a runtime table shows blockIdx%8 -> XCC is a bijection
# speedup vs baseline: 1.0045x; 1.0018x over previous
; #define LAS __attribute__((address_space(3)))
; __global__ void __launch_bounds__(512, 2) mk_fwd(Args a) {
;     extern __shared__ __attribute__((aligned(16))) unsigned char lds_raw[];
;     LAS unsigned char* lds = (LAS unsigned char*)lds_raw;
;     cg::grid_group grid = cg::this_grid();
;     volatile LAS unsigned* bst = (volatile LAS unsigned*)(lds + LDS_BYTES - 16);
;     if (threadIdx.x < 2) bst[threadIdx.x] = 0u;
;     __syncthreads();
;     XcdBarrier bar; bar.bar = nullptr; bar.x = 0; bar.st = bst;
;     int redo_ = 0;
;     for (int ph = a.ph_lo; ph < a.ph_hi; ++ph) {
;         int bid_ = blockIdx.x, G_ = gridDim.x; asm volatile("" : "+s"(bid_), "+s"(G_));
;         const int G = G_, bid = bid_;
;         unsigned char* ws = a.ws; asm volatile("" : "+s"(ws));
;         const float* x_in = (const float*)a.in[0]; const float* mem = (const float*)a.in[1]; const int* positions = (const int*)a.in[2];
;         float* X = a.out;
;         unsigned* CNT = (unsigned*)(ws + WS_CNT); float* KMEAN = (float*)(ws + WS_KMEAN); float* SSQ = (float*)(ws + WS_SSQ); f32x2* ROPE = (f32x2*)(ws + WS_ROPE);
;         bf16_t* MEMB = (bf16_t*)(ws + WS_MEMB); float* MKV = (float*)(ws + WS_MKV); f32x2* ML = (f32x2*)(ws + WS_ML);
;         bf16_t* XB = (bf16_t*)(ws + WS_XB); unsigned* LIST = (unsigned*)a.out; bf16_t* VT = (bf16_t*)((unsigned char*)a.out + 32 * MiB);
;         bf16_t* H = (bf16_t*)(ws + WS_H); bf16_t* PROJ = (bf16_t*)(ws + WS_H); bf16_t* MIX = (bf16_t*)(ws + WS_MIX); bf16_t* PART = (bf16_t*)(ws + WS_PART);
;         bf16_t* WT_MKV = (bf16_t*)(ws + WS_WT);
_Z6mk_fwd4Args:
	s_mov_b64 s[70:71], s[0:1]
	s_mov_b32 s98, 1
	s_mov_b32 s100, 0
	s_load_dwordx2 s[66:67], s[0:1], 0x1b0
	s_add_u32 s0, s70, 0x1b0
	s_addc_u32 s1, s71, 0
	v_and_b32_e32 v232, 0x3ff, v0
	v_writelane_b32 v254, s0, 0
	v_cmp_gt_u32_e32 vcc, 2, v232
	s_nop 0
	v_writelane_b32 v254, s1, 1
	s_and_saveexec_b64 s[0:1], vcc
	v_lshl_add_u32 v1, v232, 2, 0
	v_add_u32_e32 v1, 0x23ff0, v1
	v_mov_b32_e32 v2, 0
	ds_write_b32 v1, v2
	s_or_b64 exec, exec, s[0:1]
	s_load_dwordx2 s[72:73], s[70:71], 0x1a8
	s_waitcnt lgkmcnt(0)
	s_barrier
	s_cmp_ge_i32 s72, s73
	s_cbranch_scc1 .LBB0_729
	s_load_dwordx8 s[52:59], s[70:71], 0x80
	s_load_dwordx16 s[4:19], s[70:71], 0x0
	s_load_dwordx2 s[90:91], s[70:71], 0xa0
	s_load_dword s1, s[70:71], 0x1b8
	s_mul_i32 s0, s67, s66
	s_waitcnt lgkmcnt(0)
	s_add_u32 s96, s58, 0x2000000
	s_addc_u32 s97, s59, 0
	s_cmp_lg_u64 s[16:17], 0
	s_cselect_b64 s[20:21], -1, 0
	v_writelane_b32 v254, s20, 2
	s_cmp_lg_u64 s[52:53], 0
	v_lshrrev_b32_e32 v1, 20, v0
	v_writelane_b32 v254, s21, 3
	s_cselect_b64 s[20:21], -1, 0
	v_writelane_b32 v254, s20, 4
	s_cmp_lg_u64 s[10:11], 0
	v_lshrrev_b32_e32 v0, 10, v0
	v_writelane_b32 v254, s21, 5
	s_cselect_b64 s[20:21], -1, 0
	s_mul_i32 s67, s0, s1
	v_or_b32_e32 v0, v0, v1
	s_movk_i32 s0, 0x3ff
	v_writelane_b32 v254, s20, 6
	v_and_or_b32 v0, v0, s0, v232
	s_add_u32 s0, s90, 0x4000
	v_writelane_b32 v254, s21, 7
	s_addc_u32 s1, s91, 0
	v_writelane_b32 v254, s0, 8
	s_load_dwordx16 s[36:51], s[70:71], 0x40
	v_mbcnt_lo_u32_b32 v1, -1, 0
	v_writelane_b32 v254, s1, 9
	s_add_u32 s0, s4, 0x1c00
	v_writelane_b32 v254, s0, 10
	v_writelane_b32 v254, s4, 11
	s_addc_u32 s0, s5, 0
	v_mov_b32_e32 v129, 0
	v_writelane_b32 v254, s5, 12
	v_writelane_b32 v254, s6, 13
	v_writelane_b32 v254, s7, 14
	v_writelane_b32 v254, s8, 15
	v_writelane_b32 v254, s9, 16
	v_writelane_b32 v254, s10, 17
	v_writelane_b32 v254, s11, 18
	v_writelane_b32 v254, s12, 19
	v_writelane_b32 v254, s13, 20
	v_writelane_b32 v254, s14, 21
	v_writelane_b32 v254, s15, 22
	v_writelane_b32 v254, s16, 23
	v_writelane_b32 v254, s17, 24
	v_writelane_b32 v254, s18, 25
	v_writelane_b32 v254, s19, 26
	v_writelane_b32 v254, s0, 27
	s_add_i32 s0, 0, 0x11000
	v_writelane_b32 v254, s0, 28
	s_add_i32 s0, 0, 0x22804
	v_writelane_b32 v254, s0, 29
	s_add_i32 s0, 0, 0x22808
	v_writelane_b32 v254, s0, 30
	s_add_i32 s0, 0, 0x2280c
	v_writelane_b32 v254, s0, 31
	s_add_i32 s0, 0, 0x22810
	v_writelane_b32 v254, s0, 32
	s_add_i32 s0, 0, 0x22814
	v_writelane_b32 v254, s0, 33
	s_add_i32 s0, 0, 0x22818
	v_writelane_b32 v254, s0, 34
	s_add_i32 s0, 0, 0x2281c
	v_writelane_b32 v254, s0, 35
	s_add_i32 s0, 0, 0x227fc
	v_writelane_b32 v254, s0, 36
	s_add_i32 s0, 0, 0x23ff0
	v_writelane_b32 v254, s0, 37
	s_add_i32 s0, 0, 0x23ff4
	v_writelane_b32 v254, s0, 38
	s_mov_b32 s0, 0
	v_writelane_b32 v254, s0, 39
	v_cmp_eq_u32_e64 s[0:1], 0, v232
	s_mov_b32 s14, s72
	s_movk_i32 s86, 0x110
	v_writelane_b32 v254, s0, 40
	s_mov_b32 s69, 0xf149f2ca
	s_mov_b32 s87, 0x3e0293ee
	v_writelane_b32 v254, s1, 41
	v_cmp_eq_u32_e64 s[0:1], 0, v0
	v_mov_b32_e32 v233, 1
	v_mov_b32_e32 v234, 0x358637bd
	v_writelane_b32 v254, s0, 42
	s_mov_b32 s33, 0xf800000
	v_mov_b32_e32 v235, 0x260
	v_writelane_b32 v254, s1, 43
	v_writelane_b32 v254, s2, 44
	v_writelane_b32 v254, s70, 45
	s_movk_i32 s62, 0x1000
	s_mov_b32 s63, 0xb000
	v_writelane_b32 v254, s71, 46
	v_writelane_b32 v254, s90, 47
	v_mov_b32_e32 v236, 0x2000
	v_mbcnt_hi_u32_b32 v237, -1, v1
	v_writelane_b32 v254, s91, 48
	v_writelane_b32 v254, s96, 49
	v_mov_b32_e32 v238, 0xff800000
	v_mov_b32_e32 v239, 0xffffea00
	v_writelane_b32 v254, s97, 50
	v_writelane_b32 v254, s66, 51
	v_mov_b32_e32 v240, 0x80
	v_mov_b32_e32 v241, 0x5f
	v_writelane_b32 v254, s67, 52
	v_writelane_b32 v254, s72, 53
	v_mov_b32_e32 v242, 0x67
	v_mov_b32_e32 v243, 0x6f
	v_writelane_b32 v254, s73, 54
	v_mov_b32_e32 v244, 0x77
	v_mov_b32_e32 v245, 0x7f
	s_movk_i32 s3, 0x2c00
	s_mov_b64 s[78:79], 0
	s_mov_b32 s75, 0
	s_mov_b64 s[76:77], 0x80
	v_writelane_b32 v254, s67, 55
	s_branch .LBB0_8

; __global__ void __launch_bounds__(512, 2) mk_fwd(Args a) {
;     ...
;         if (ph + 1 < a.ph_hi) {
;             if (ph == a.ph_lo) { grid.sync(); bar = xcd_barrier_post((unsigned*)(a.ws + WS_BAR), bst); }
;             else xcd_barrier(bar);
;         }
.LBB0_658:
	s_mov_b32 s100, s35
	s_cmp_lg_u32 s35, 1
	s_cbranch_scc1 .Lmap_chk_done
	v_cmp_eq_u32_e64 s[98:99], 0, v232
	s_nop 3
	s_and_saveexec_b64 s[0:1], s[98:99]
	s_cbranch_execz .Lmap_skip_atomic
	v_readlane_b32 s98, v254, 44
	s_nop 3
	s_and_b32 s98, s98, 7
	s_lshl_b32 s98, s98, 2
	v_mov_b32_e32 v0, s98
	v_readlane_b32 s98, v254, 39
	s_nop 3
	s_lshl_b32 s98, 1, s98
	v_mov_b32_e32 v1, s98
	v_readlane_b32 s98, v254, 8
	v_readlane_b32 s99, v254, 9
	s_nop 4
	global_atomic_or v0, v1, s[98:99] offset:768
.Lmap_skip_atomic:
	s_mov_b64 exec, s[0:1]
	s_mov_b32 s98, 1
.Lmap_chk_done:
	s_cmp_lg_u32 s35, 2
	s_cbranch_scc1 .Lmap_rd_done
	v_readlane_b32 s0, v254, 8
	v_readlane_b32 s1, v254, 9
	v_and_b32_e32 v0, 7, v237
	v_lshlrev_b32_e32 v0, 2, v0
	s_nop 4
	global_load_dword v0, v0, s[0:1] offset:768 sc1
	s_waitcnt vmcnt(0)
	v_bcnt_u32_b32 v1, v0, 0
	v_cmp_ne_u32_e64 s[0:1], 1, v1
	v_readlane_b32 s99, v0, 0
	s_nop 3
	v_readlane_b32 s98, v0, 1
	s_nop 3
	s_or_b32 s99, s99, s98
	v_readlane_b32 s98, v0, 2
	s_nop 3
	s_or_b32 s99, s99, s98
	v_readlane_b32 s98, v0, 3
	s_nop 3
	s_or_b32 s99, s99, s98
	v_readlane_b32 s98, v0, 4
	s_nop 3
	s_or_b32 s99, s99, s98
	v_readlane_b32 s98, v0, 5
	s_nop 3
	s_or_b32 s99, s99, s98
	v_readlane_b32 s98, v0, 6
	s_nop 3
	s_or_b32 s99, s99, s98
	v_readlane_b32 s98, v0, 7
	s_nop 3
	s_or_b32 s99, s99, s98
	s_bcnt1_i32_b32 s99, s99
	s_mov_b32 s98, 1
	s_cmp_lg_u64 s[0:1], 0
	s_cbranch_scc1 .Lmap_rd_done
	s_cmp_lg_u32 s99, 8
	s_cbranch_scc1 .Lmap_rd_done
	s_mov_b32 s98, 0

; __device__ __forceinline__ unsigned xb_ld(unsigned* p)              { return __hip_atomic_load(p, __ATOMIC_RELAXED, __HIP_MEMORY_SCOPE_AGENT); }
; __device__ __forceinline__ unsigned xb_add(unsigned* p, unsigned v) { return __hip_atomic_fetch_add(p, v, __ATOMIC_RELAXED, __HIP_MEMORY_SCOPE_AGENT); }
; #define XB_SPIN(cond, bar) do { unsigned _sp = 0; while (cond) { __builtin_amdgcn_s_sleep(1); \
;     if ((++_sp & 255u) == 0u) { if (xb_ld(&(bar)[XB_TMO])) break; if (_sp > XB_SPIN_CAP) { atomicAdd(&(bar)[XB_TMO], 1u); break; } } } } while (0)
; __device__ __forceinline__ void xcd_barrier(const XcdBarrier& b) {
;     ...
;         const unsigned old = xb_add(&bar[XB_XSUB(b.x)], 1u);
;         const unsigned gen = old / nloc;
;         if (old + 1u == (gen + 1u) * nloc) {
;             __builtin_amdgcn_fence(__ATOMIC_RELEASE, "agent");
;             asm volatile("s_waitcnt vmcnt(0)" ::: "memory");
;             const unsigned og = xb_add(&bar[XB_TOP], 1u);
;             const unsigned tg = og / nx;
;             if (og + 1u == (tg + 1u) * nx) xb_add(&bar[XB_TOPGEN], 1u);
;             else XB_SPIN(xb_ld(&bar[XB_TOPGEN]) == tg, bar);
.LBB0_698:
	s_andn2_saveexec_b64 s[6:7], s[6:7]
	s_cbranch_execz .LBB0_714
	s_cmp_lg_u32 s98, 0
	s_cbranch_scc1 .Lbar_full
	s_mov_b32 s99, 0x181e04
	s_bitcmp1_b32 s99, s100
	s_cbranch_scc1 .Lbar_local
.Lbar_full:
	buffer_wbl2 sc1
	s_waitcnt lgkmcnt(0)
	s_waitcnt vmcnt(0)
	v_mov_b32_e32 v1, 0x3000
	global_atomic_add v1, v1, v233, s[78:79] offset:1024 sc0
	v_cvt_f32_u32_e32 v2, v0
	v_sub_u32_e32 v3, 0, v0
	s_add_u32 s6, s78, 0x3500
	s_addc_u32 s7, s79, 0
	v_rcp_iflag_f32_e32 v2, v2
	s_mov_b64 s[10:11], -1
	v_mul_f32_e32 v2, 0x4f7ffffe, v2
	v_cvt_u32_f32_e32 v2, v2
	v_mul_lo_u32 v3, v3, v2
	v_mul_hi_u32 v3, v2, v3
	v_add_u32_e32 v2, v2, v3
	s_waitcnt vmcnt(0)
	v_mul_hi_u32 v2, v1, v2
	v_mul_lo_u32 v3, v2, v0
	v_sub_u32_e32 v3, v1, v3
	v_cmp_ge_u32_e32 vcc, v3, v0
	v_add_u32_e32 v4, 1, v2
	v_add_u32_e32 v1, 1, v1
	v_cndmask_b32_e32 v2, v2, v4, vcc
	v_sub_u32_e32 v4, v3, v0
	v_cndmask_b32_e32 v3, v3, v4, vcc
	v_cmp_ge_u32_e32 vcc, v3, v0
	v_add_u32_e32 v3, 1, v2
	s_nop 0
	v_cndmask_b32_e32 v2, v2, v3, vcc
	v_mul_lo_u32 v3, v0, v2
	v_add_u32_e32 v0, v3, v0
	v_cmp_ne_u32_e32 vcc, v1, v0
	v_mov_b64_e32 v[0:1], s[6:7]
	s_and_saveexec_b64 s[8:9], vcc
	s_cbranch_execz .LBB0_711
	global_load_dword v0, v129, s[6:7] sc1
	s_mov_b64 s[28:29], 0
	s_waitcnt vmcnt(0)
	v_cmp_eq_u32_e32 vcc, v0, v2
	s_and_saveexec_b64 s[12:13], vcc
	s_cbranch_execz .LBB0_710
	s_add_u32 s10, s78, 0x200
	s_addc_u32 s11, s79, 0
	s_mov_b32 s15, 1
	s_branch .LBB0_703

; __device__ __forceinline__ unsigned xb_add(unsigned* p, unsigned v) { return __hip_atomic_fetch_add(p, v, __ATOMIC_RELAXED, __HIP_MEMORY_SCOPE_AGENT); }
; __device__ __forceinline__ void xcd_barrier(const XcdBarrier& b) {
;     ...
;             __builtin_amdgcn_fence(__ATOMIC_ACQUIRE, "agent");
;             xb_add(&bar[XB_XGEN(b.x)], 1u);
;             asm volatile("s_waitcnt vmcnt(0)" ::: "memory");
.Lbar_local:
	s_waitcnt vmcnt(0)
	buffer_inv sc1
	global_atomic_add v236, v233, s[4:5] offset:1024
	s_waitcnt vmcnt(0)

; __global__ void __launch_bounds__(512, 2) mk_fwd(Args a) {
	.amdhsa_kernel _Z6mk_fwd4Args
		.amdhsa_group_segment_fixed_size 0
		.amdhsa_private_segment_fixed_size 0
		.amdhsa_kernarg_size 688
		.amdhsa_user_sgpr_count 2
		.amdhsa_user_sgpr_dispatch_ptr 0
		.amdhsa_user_sgpr_queue_ptr 0
		.amdhsa_user_sgpr_kernarg_segment_ptr 1
		.amdhsa_user_sgpr_dispatch_id 0
		.amdhsa_user_sgpr_kernarg_preload_length 0
		.amdhsa_user_sgpr_kernarg_preload_offset 0
		.amdhsa_user_sgpr_private_segment_size 0
		.amdhsa_uses_dynamic_stack 0
		.amdhsa_enable_private_segment 0
		.amdhsa_system_sgpr_workgroup_id_x 1
		.amdhsa_system_sgpr_workgroup_id_y 0
		.amdhsa_system_sgpr_workgroup_id_z 0
		.amdhsa_system_sgpr_workgroup_info 0
		.amdhsa_system_vgpr_workitem_id 2
		.amdhsa_next_free_vgpr 256
		.amdhsa_next_free_sgpr 101
		.amdhsa_accum_offset 256
		.amdhsa_reserve_vcc 1
		.amdhsa_float_round_mode_32 0
		.amdhsa_float_round_mode_16_64 0
		.amdhsa_float_denorm_mode_32 3
		.amdhsa_float_denorm_mode_16_64 3
		.amdhsa_dx10_clamp 1
		.amdhsa_ieee_mode 1
		.amdhsa_fp16_overflow 0
		.amdhsa_tg_split 0
		.amdhsa_exception_fp_ieee_invalid_op 0
		.amdhsa_exception_fp_denorm_src 0
		.amdhsa_exception_fp_ieee_div_zero 0
		.amdhsa_exception_fp_ieee_overflow 0
		.amdhsa_exception_fp_ieee_underflow 0
		.amdhsa_exception_fp_ieee_inexact 0
		.amdhsa_exception_int_div_zero 0
	.end_amdhsa_kernel

; __global__ void __launch_bounds__(512, 2) mk_fwd(Args a) {
amdhsa.kernels:
  - .agpr_count:     0
    .args:
      - .offset:         0
        .size:           432
        .value_kind:     by_value
      - .offset:         432
        .size:           4
        .value_kind:     hidden_block_count_x
      - .offset:         436
        .size:           4
        .value_kind:     hidden_block_count_y
      - .offset:         440
        .size:           4
        .value_kind:     hidden_block_count_z
      - .offset:         444
        .size:           2
        .value_kind:     hidden_group_size_x
      - .offset:         446
        .size:           2
        .value_kind:     hidden_group_size_y
      - .offset:         448
        .size:           2
        .value_kind:     hidden_group_size_z
      - .offset:         450
        .size:           2
        .value_kind:     hidden_remainder_x
      - .offset:         452
        .size:           2
        .value_kind:     hidden_remainder_y
      - .offset:         454
        .size:           2
        .value_kind:     hidden_remainder_z
      - .offset:         472
        .size:           8
        .value_kind:     hidden_global_offset_x
      - .offset:         480
        .size:           8
        .value_kind:     hidden_global_offset_y
      - .offset:         488
        .size:           8
        .value_kind:     hidden_global_offset_z
      - .offset:         496
        .size:           2
        .value_kind:     hidden_grid_dims
      - .offset:         520
        .size:           8
        .value_kind:     hidden_multigrid_sync_arg
      - .offset:         552
        .size:           4
        .value_kind:     hidden_dynamic_lds_size
    .group_segment_fixed_size: 0
    .kernarg_segment_align: 8
    .kernarg_segment_size: 688
    .language:       OpenCL C
    .language_version:
      - 2
      - 0
    .max_flat_workgroup_size: 512
    .name:           _Z6mk_fwd4Args
    .private_segment_fixed_size: 0
    .sgpr_count:     107
    .sgpr_spill_count: 90
    .symbol:         _Z6mk_fwd4Args.kd
    .uniform_work_group_size: 1
    .uses_dynamic_stack: false
    .vgpr_count:     256
    .vgpr_spill_count: 0
    .wavefront_size: 64
